# conv phase: read-once input tile fill loads marked nt (on top of final-norm nt loads)
# baseline (speedup 1.0000x reference)
; #define LAS __attribute__((address_space(3)))
; __device__ __forceinline__ void conv_phase(LAS unsigned char* lds, const bf16_t* U, bf16_t* C, const float* wdw, const float* bdw, const float* lng, const float* lnb,
;                                            int first, int stride, int end, int tid, int wave, int lane) {
;     ...
;     for (int tile = first; tile < end; tile += stride) {
;         const int t0 = tile * TT, tin = t0 % SEQ;
;         for (int idx = tid; idx < ROWS * 128; idx += NTHREADS) {
;             const int row = idx >> 7, ch = idx & 127;
;             u32x4 v = (u32x4){0u, 0u, 0u, 0u};
;             if (tin + row - (CW - 1) >= 0) v = *(const u32x4*)(U + (size_t)(t0 + row - (CW - 1)) * D + ch * 8);
;             *(LAS u32x4*)(lds + row * 2048 + ch * 16) = v;
;         }
;         asm volatile("s_waitcnt lgkmcnt(0)" ::: "memory"); __builtin_amdgcn_s_barrier(); asm volatile("" ::: "memory");
.LBB0_90:
	v_lshlrev_b32_e32 v141, 5, v140
	s_and_saveexec_b64 s[4:5], vcc
	s_cbranch_execz .LBB0_89
	v_ashrrev_i32_e32 v0, 31, v141
	v_lshrrev_b32_e32 v0, 20, v0
	v_add_u32_e32 v0, v141, v0
	v_and_b32_e32 v0, 0xfffff000, v0
	v_sub_u32_e32 v0, v0, v141
	v_add_u32_e32 v4, 29, v0
	v_subrev_u32_e32 v5, 30, v141
	v_lshrrev_b32_e32 v6, 7, v132
	v_add_u32_e32 v0, v5, v6
	v_ashrrev_i32_e32 v1, 31, v0
	v_lshl_add_u32 v2, v6, 11, v135
	v_lshlrev_b64 v[0:1], 11, v[0:1]
	v_add_u32_e32 v3, 0x10000, v2
	s_mov_b64 s[28:29], 0x2000
	v_lshl_add_u64 v[0:1], v[94:95], 0, v[0:1]
	v_add_u32_e32 v7, 0, v6
	v_cmp_gt_i32_e64 s[40:41], v7, v4
	v_mov_b32_e32 v8, 0
	v_mov_b32_e32 v9, 0
	v_mov_b32_e32 v10, 0
	v_mov_b32_e32 v11, 0
	s_and_saveexec_b64 s[30:31], s[40:41]
	global_load_dwordx4 v[8:11], v[0:1], off nt
	s_mov_b64 exec, s[30:31]
	v_lshl_add_u64 v[0:1], v[0:1], 0, s[28:29]
	v_add_u32_e32 v7, 4, v6
	v_cmp_gt_i32_e64 s[40:41], v7, v4
	v_mov_b32_e32 v12, 0
	v_mov_b32_e32 v13, 0
	v_mov_b32_e32 v14, 0
	v_mov_b32_e32 v15, 0
	s_and_saveexec_b64 s[30:31], s[40:41]
	global_load_dwordx4 v[12:15], v[0:1], off nt
	s_mov_b64 exec, s[30:31]
	v_lshl_add_u64 v[0:1], v[0:1], 0, s[28:29]
	v_add_u32_e32 v7, 8, v6
	v_cmp_gt_i32_e64 s[40:41], v7, v4
	v_mov_b32_e32 v16, 0
	v_mov_b32_e32 v17, 0
	v_mov_b32_e32 v18, 0
	v_mov_b32_e32 v19, 0
	s_and_saveexec_b64 s[30:31], s[40:41]
	global_load_dwordx4 v[16:19], v[0:1], off nt
	s_mov_b64 exec, s[30:31]
	v_lshl_add_u64 v[0:1], v[0:1], 0, s[28:29]
	v_add_u32_e32 v7, 12, v6
	v_cmp_gt_i32_e64 s[40:41], v7, v4
	v_mov_b32_e32 v20, 0
	v_mov_b32_e32 v21, 0
	v_mov_b32_e32 v22, 0
	v_mov_b32_e32 v23, 0
	s_and_saveexec_b64 s[30:31], s[40:41]
	global_load_dwordx4 v[20:23], v[0:1], off nt
	s_mov_b64 exec, s[30:31]
	v_lshl_add_u64 v[0:1], v[0:1], 0, s[28:29]
	v_add_u32_e32 v7, 16, v6
	v_cmp_gt_i32_e64 s[40:41], v7, v4
	v_mov_b32_e32 v24, 0
	v_mov_b32_e32 v25, 0
	v_mov_b32_e32 v26, 0
	v_mov_b32_e32 v27, 0
	s_and_saveexec_b64 s[30:31], s[40:41]
	global_load_dwordx4 v[24:27], v[0:1], off nt
	s_mov_b64 exec, s[30:31]
	v_lshl_add_u64 v[0:1], v[0:1], 0, s[28:29]
	v_add_u32_e32 v7, 20, v6
	v_cmp_gt_i32_e64 s[40:41], v7, v4
	v_mov_b32_e32 v28, 0
	v_mov_b32_e32 v29, 0
	v_mov_b32_e32 v30, 0
	v_mov_b32_e32 v31, 0
	s_and_saveexec_b64 s[30:31], s[40:41]
	global_load_dwordx4 v[28:31], v[0:1], off nt
	s_mov_b64 exec, s[30:31]
	v_lshl_add_u64 v[0:1], v[0:1], 0, s[28:29]
	v_add_u32_e32 v7, 24, v6
	v_cmp_gt_i32_e64 s[40:41], v7, v4
	v_mov_b32_e32 v32, 0
	v_mov_b32_e32 v33, 0
	v_mov_b32_e32 v34, 0
	v_mov_b32_e32 v35, 0
	s_and_saveexec_b64 s[30:31], s[40:41]
	global_load_dwordx4 v[32:35], v[0:1], off nt
	s_mov_b64 exec, s[30:31]
	v_lshl_add_u64 v[0:1], v[0:1], 0, s[28:29]
	v_add_u32_e32 v7, 28, v6
	v_cmp_gt_i32_e64 s[40:41], v7, v4
	v_mov_b32_e32 v36, 0
	v_mov_b32_e32 v37, 0
	v_mov_b32_e32 v38, 0
	v_mov_b32_e32 v39, 0
	s_and_saveexec_b64 s[30:31], s[40:41]
	global_load_dwordx4 v[36:39], v[0:1], off nt
	s_mov_b64 exec, s[30:31]
	v_lshl_add_u64 v[0:1], v[0:1], 0, s[28:29]
	v_add_u32_e32 v7, 32, v6
	v_cmp_gt_i32_e64 s[40:41], v7, v4
	v_mov_b32_e32 v40, 0
	v_mov_b32_e32 v41, 0
	v_mov_b32_e32 v42, 0
	v_mov_b32_e32 v43, 0
	s_and_saveexec_b64 s[30:31], s[40:41]
	global_load_dwordx4 v[40:43], v[0:1], off nt
	s_mov_b64 exec, s[30:31]
	v_lshl_add_u64 v[0:1], v[0:1], 0, s[28:29]
	v_add_u32_e32 v7, 36, v6
	v_cmp_gt_i32_e64 s[40:41], v7, v4
	v_mov_b32_e32 v44, 0
	v_mov_b32_e32 v45, 0
	v_mov_b32_e32 v46, 0
	v_mov_b32_e32 v47, 0
	s_and_saveexec_b64 s[30:31], s[40:41]
	global_load_dwordx4 v[44:47], v[0:1], off nt
	s_mov_b64 exec, s[30:31]
	v_lshl_add_u64 v[0:1], v[0:1], 0, s[28:29]
	v_add_u32_e32 v7, 40, v6
	v_cmp_gt_i32_e64 s[40:41], v7, v4
	v_mov_b32_e32 v48, 0
	v_mov_b32_e32 v49, 0
	v_mov_b32_e32 v50, 0
	v_mov_b32_e32 v51, 0
	s_and_saveexec_b64 s[30:31], s[40:41]
	global_load_dwordx4 v[48:51], v[0:1], off nt
	s_mov_b64 exec, s[30:31]
	v_lshl_add_u64 v[0:1], v[0:1], 0, s[28:29]
	v_add_u32_e32 v7, 44, v6
	v_cmp_gt_i32_e64 s[40:41], v7, v4
	v_mov_b32_e32 v52, 0
	v_mov_b32_e32 v53, 0
	v_mov_b32_e32 v54, 0
	v_mov_b32_e32 v55, 0
	s_and_saveexec_b64 s[30:31], s[40:41]
	global_load_dwordx4 v[52:55], v[0:1], off nt
	s_mov_b64 exec, s[30:31]
	v_lshl_add_u64 v[0:1], v[0:1], 0, s[28:29]
	v_add_u32_e32 v7, 48, v6
	v_cmp_gt_i32_e64 s[40:41], v7, v4
	v_mov_b32_e32 v56, 0
	v_mov_b32_e32 v57, 0
	v_mov_b32_e32 v58, 0
	v_mov_b32_e32 v59, 0
	s_and_saveexec_b64 s[30:31], s[40:41]
	global_load_dwordx4 v[56:59], v[0:1], off nt
	s_mov_b64 exec, s[30:31]
	v_lshl_add_u64 v[0:1], v[0:1], 0, s[28:29]
	v_add_u32_e32 v7, 52, v6
	v_cmp_gt_i32_e64 s[40:41], v7, v4
	v_mov_b32_e32 v60, 0
	v_mov_b32_e32 v61, 0
	v_mov_b32_e32 v62, 0
	v_mov_b32_e32 v63, 0
	s_and_saveexec_b64 s[30:31], s[40:41]
	global_load_dwordx4 v[60:63], v[0:1], off nt
	s_mov_b64 exec, s[30:31]
	v_lshl_add_u64 v[0:1], v[0:1], 0, s[28:29]
	v_add_u32_e32 v7, 56, v6
	v_cmp_gt_i32_e64 s[40:41], v7, v4
	v_mov_b32_e32 v64, 0
	v_mov_b32_e32 v65, 0
	v_mov_b32_e32 v66, 0
	v_mov_b32_e32 v67, 0
	s_and_saveexec_b64 s[30:31], s[40:41]
	global_load_dwordx4 v[64:67], v[0:1], off nt
	s_mov_b64 exec, s[30:31]
	v_lshl_add_u64 v[0:1], v[0:1], 0, s[28:29]
	v_add_u32_e32 v7, 60, v6
	v_cmp_gt_i32_e64 s[40:41], v7, v4
	v_mov_b32_e32 v68, 0
	v_mov_b32_e32 v69, 0
	v_mov_b32_e32 v70, 0
	v_mov_b32_e32 v71, 0
	v_cmp_gt_i32_e64 s[30:31], 2, v6
	s_nop 1
	s_and_b64 s[40:41], s[40:41], s[30:31]
	s_and_saveexec_b64 s[30:31], s[40:41]
	global_load_dwordx4 v[68:71], v[0:1], off nt
	s_mov_b64 exec, s[30:31]
	s_waitcnt vmcnt(0)
	ds_write_b128 v2, v[8:11]
	ds_write_b128 v2, v[12:15] offset:8192
	ds_write_b128 v2, v[16:19] offset:16384
	ds_write_b128 v2, v[20:23] offset:24576
	ds_write_b128 v2, v[24:27] offset:32768
	ds_write_b128 v2, v[28:31] offset:40960
	ds_write_b128 v2, v[32:35] offset:49152
	ds_write_b128 v2, v[36:39] offset:57344
	ds_write_b128 v3, v[40:43]
	ds_write_b128 v3, v[44:47] offset:8192
	ds_write_b128 v3, v[48:51] offset:16384
	ds_write_b128 v3, v[52:55] offset:24576
	ds_write_b128 v3, v[56:59] offset:32768
	ds_write_b128 v3, v[60:63] offset:40960
	ds_write_b128 v3, v[64:67] offset:49152
	v_cmp_gt_i32_e64 s[40:41], 2, v6
	s_nop 1
	s_and_saveexec_b64 s[30:31], s[40:41]
	ds_write_b128 v3, v[68:71] offset:57344
	s_mov_b64 exec, s[30:31]
	s_branch .LBB0_89
